# code placement: the ten GEMM K-loop heads aligned to 64 bytes
# speedup vs baseline: 1.0007x; 1.0007x over previous
.LBB11_220:
	s_add_u32 s12, s30, s59
	s_addc_u32 s13, s31, 0
	s_and_b64 s[18:19], s[16:17], exec
	s_cselect_b32 s7, s13, s21
	s_cselect_b32 s26, s12, s20
	s_add_u32 s18, s34, s57
	s_addc_u32 s19, s35, 0
	s_and_b64 s[24:25], s[16:17], exec
	s_cselect_b32 s27, s19, s23
	s_cselect_b32 s60, s18, s22
	s_add_u32 s20, s20, 0x40080
	s_addc_u32 s21, s21, 0
	s_add_u32 s61, s22, 0x100
	v_mov_b32_e32 v0, 0
	s_addc_u32 s62, s23, 0
	s_mov_b32 s63, -2
	v_mov_b64_e32 v[0:1], 0
	v_mov_b64_e32 v[2:3], 0
	v_mov_b64_e32 v[4:5], 0
	v_mov_b64_e32 v[6:7], 0
	v_mov_b64_e32 v[8:9], 0
	v_mov_b64_e32 v[10:11], 0
	v_mov_b64_e32 v[12:13], 0
	v_mov_b64_e32 v[14:15], 0
	v_mov_b64_e32 v[16:17], 0
	v_mov_b64_e32 v[18:19], 0
	v_mov_b64_e32 v[20:21], 0
	v_mov_b64_e32 v[22:23], 0
	v_mov_b64_e32 v[24:25], 0
	v_mov_b64_e32 v[26:27], 0
	v_mov_b64_e32 v[28:29], 0
	v_mov_b64_e32 v[30:31], 0
	v_mov_b64_e32 v[32:33], 0
	v_mov_b64_e32 v[34:35], 0
	v_mov_b64_e32 v[36:37], 0
	v_mov_b64_e32 v[38:39], 0
	v_mov_b64_e32 v[40:41], 0
	v_mov_b64_e32 v[42:43], 0
	v_mov_b64_e32 v[44:45], 0
	v_mov_b64_e32 v[46:47], 0
	v_mov_b64_e32 v[48:49], 0
	v_mov_b64_e32 v[50:51], 0
	v_mov_b64_e32 v[52:53], 0
	v_mov_b64_e32 v[54:55], 0
	v_mov_b64_e32 v[56:57], 0
	v_mov_b64_e32 v[58:59], 0
	v_mov_b64_e32 v[60:61], 0
	v_mov_b64_e32 v[62:63], 0
	v_mov_b64_e32 v[64:65], 0
	v_mov_b64_e32 v[66:67], 0
	v_mov_b64_e32 v[68:69], 0
	v_mov_b64_e32 v[70:71], 0
	v_mov_b64_e32 v[72:73], 0
	v_mov_b64_e32 v[74:75], 0
	v_mov_b64_e32 v[76:77], 0
	v_mov_b64_e32 v[78:79], 0
	v_mov_b64_e32 v[80:81], 0
	v_mov_b64_e32 v[82:83], 0
	v_mov_b64_e32 v[84:85], 0
	v_mov_b64_e32 v[86:87], 0
	v_mov_b64_e32 v[88:89], 0
	v_mov_b64_e32 v[90:91], 0
	v_mov_b64_e32 v[92:93], 0
	v_mov_b64_e32 v[94:95], 0
	v_mov_b64_e32 v[96:97], 0
	v_mov_b64_e32 v[98:99], 0
	v_mov_b64_e32 v[100:101], 0
	v_mov_b64_e32 v[102:103], 0
	v_mov_b64_e32 v[104:105], 0
	v_mov_b64_e32 v[106:107], 0
	v_mov_b64_e32 v[108:109], 0
	v_mov_b64_e32 v[110:111], 0
	v_mov_b64_e32 v[112:113], 0
	v_mov_b64_e32 v[114:115], 0
	v_mov_b64_e32 v[116:117], 0
	v_mov_b64_e32 v[118:119], 0
	v_mov_b64_e32 v[120:121], 0
	v_mov_b64_e32 v[122:123], 0
	v_mov_b64_e32 v[124:125], 0
	v_mov_b64_e32 v[126:127], 0
	.p2align	6

.LBB11_925:
	v_readlane_b32 s0, v243, 26
	s_add_u32 s18, s0, s44
	v_readlane_b32 s0, v243, 27
	s_addc_u32 s19, s0, 0
	s_and_b64 s[0:1], s[16:17], exec
	s_cselect_b32 s8, s19, s23
	s_cselect_b32 s9, s18, s22
	s_add_u32 s20, s30, s43
	s_addc_u32 s21, s31, 0
	s_and_b64 s[0:1], s[16:17], exec
	s_cselect_b32 s40, s21, s25
	s_cselect_b32 s46, s20, s24
	s_add_u32 s22, s22, 0x40080
	s_addc_u32 s23, s23, 0
	s_add_u32 s47, s24, 0x100
	v_mov_b32_e32 v2, 0
	s_addc_u32 s56, s25, 0
	s_mov_b32 s57, -2
	s_waitcnt lgkmcnt(0)
	v_mov_b64_e32 v[2:3], 0
	v_mov_b64_e32 v[4:5], 0
	v_mov_b64_e32 v[6:7], 0
	v_mov_b64_e32 v[8:9], 0
	v_mov_b64_e32 v[10:11], 0
	v_mov_b64_e32 v[12:13], 0
	v_mov_b64_e32 v[14:15], 0
	v_mov_b64_e32 v[16:17], 0
	v_mov_b64_e32 v[18:19], 0
	v_mov_b64_e32 v[20:21], 0
	v_mov_b64_e32 v[22:23], 0
	v_mov_b64_e32 v[24:25], 0
	v_mov_b64_e32 v[26:27], 0
	v_mov_b64_e32 v[28:29], 0
	v_mov_b64_e32 v[30:31], 0
	v_mov_b64_e32 v[32:33], 0
	v_mov_b64_e32 v[34:35], 0
	v_mov_b64_e32 v[36:37], 0
	v_mov_b64_e32 v[38:39], 0
	v_mov_b64_e32 v[40:41], 0
	v_mov_b64_e32 v[42:43], 0
	v_mov_b64_e32 v[44:45], 0
	v_mov_b64_e32 v[46:47], 0
	v_mov_b64_e32 v[48:49], 0
	v_mov_b64_e32 v[50:51], 0
	v_mov_b64_e32 v[52:53], 0
	v_mov_b64_e32 v[54:55], 0
	v_mov_b64_e32 v[56:57], 0
	v_mov_b64_e32 v[58:59], 0
	v_mov_b64_e32 v[60:61], 0
	v_mov_b64_e32 v[62:63], 0
	v_mov_b64_e32 v[64:65], 0
	v_mov_b64_e32 v[66:67], 0
	v_mov_b64_e32 v[68:69], 0
	v_mov_b64_e32 v[70:71], 0
	v_mov_b64_e32 v[72:73], 0
	v_mov_b64_e32 v[74:75], 0
	v_mov_b64_e32 v[76:77], 0
	v_mov_b64_e32 v[78:79], 0
	v_mov_b64_e32 v[80:81], 0
	v_mov_b64_e32 v[82:83], 0
	v_mov_b64_e32 v[84:85], 0
	v_mov_b64_e32 v[86:87], 0
	v_mov_b64_e32 v[88:89], 0
	v_mov_b64_e32 v[90:91], 0
	v_mov_b64_e32 v[92:93], 0
	v_mov_b64_e32 v[94:95], 0
	v_mov_b64_e32 v[96:97], 0
	v_mov_b64_e32 v[98:99], 0
	v_mov_b64_e32 v[100:101], 0
	v_mov_b64_e32 v[102:103], 0
	v_mov_b64_e32 v[104:105], 0
	v_mov_b64_e32 v[106:107], 0
	v_mov_b64_e32 v[108:109], 0
	v_mov_b64_e32 v[110:111], 0
	v_mov_b64_e32 v[112:113], 0
	v_mov_b64_e32 v[114:115], 0
	v_mov_b64_e32 v[116:117], 0
	v_mov_b64_e32 v[118:119], 0
	v_mov_b64_e32 v[120:121], 0
	v_mov_b64_e32 v[122:123], 0
	v_mov_b64_e32 v[124:125], 0
	v_mov_b64_e32 v[126:127], 0
	v_mov_b64_e32 v[128:129], 0
	.p2align	6

.LBB11_1171:
	s_add_u32 s24, s66, s91
	s_addc_u32 s25, s67, 0
	s_and_b64 s[0:1], s[22:23], exec
	s_cselect_b32 s9, s25, s17
	s_cselect_b32 s68, s24, s16
	s_add_u32 s26, s36, s90
	s_addc_u32 s27, s37, 0
	s_and_b64 s[0:1], s[22:23], exec
	s_cselect_b32 s69, s27, s29
	s_cselect_b32 s70, s26, s28
	s_add_u32 s16, s16, 0x40080
	s_addc_u32 s17, s17, 0
	s_add_u32 s71, s28, 0x100
	v_mov_b32_e32 v2, 0
	s_addc_u32 vcc_lo, s29, 0
	s_mov_b32 vcc_hi, -2
	s_waitcnt lgkmcnt(0)
	v_mov_b64_e32 v[2:3], 0
	v_mov_b64_e32 v[4:5], 0
	v_mov_b64_e32 v[6:7], 0
	v_mov_b64_e32 v[8:9], 0
	v_mov_b64_e32 v[10:11], 0
	v_mov_b64_e32 v[12:13], 0
	v_mov_b64_e32 v[14:15], 0
	v_mov_b64_e32 v[16:17], 0
	v_mov_b64_e32 v[18:19], 0
	v_mov_b64_e32 v[20:21], 0
	v_mov_b64_e32 v[22:23], 0
	v_mov_b64_e32 v[24:25], 0
	v_mov_b64_e32 v[26:27], 0
	v_mov_b64_e32 v[28:29], 0
	v_mov_b64_e32 v[30:31], 0
	v_mov_b64_e32 v[32:33], 0
	v_mov_b64_e32 v[34:35], 0
	v_mov_b64_e32 v[36:37], 0
	v_mov_b64_e32 v[38:39], 0
	v_mov_b64_e32 v[40:41], 0
	v_mov_b64_e32 v[42:43], 0
	v_mov_b64_e32 v[44:45], 0
	v_mov_b64_e32 v[46:47], 0
	v_mov_b64_e32 v[48:49], 0
	v_mov_b64_e32 v[50:51], 0
	v_mov_b64_e32 v[52:53], 0
	v_mov_b64_e32 v[54:55], 0
	v_mov_b64_e32 v[56:57], 0
	v_mov_b64_e32 v[58:59], 0
	v_mov_b64_e32 v[60:61], 0
	v_mov_b64_e32 v[62:63], 0
	v_mov_b64_e32 v[64:65], 0
	v_mov_b64_e32 v[66:67], 0
	v_mov_b64_e32 v[68:69], 0
	v_mov_b64_e32 v[70:71], 0
	v_mov_b64_e32 v[72:73], 0
	v_mov_b64_e32 v[74:75], 0
	v_mov_b64_e32 v[76:77], 0
	v_mov_b64_e32 v[78:79], 0
	v_mov_b64_e32 v[80:81], 0
	v_mov_b64_e32 v[82:83], 0
	v_mov_b64_e32 v[84:85], 0
	v_mov_b64_e32 v[86:87], 0
	v_mov_b64_e32 v[88:89], 0
	v_mov_b64_e32 v[90:91], 0
	v_mov_b64_e32 v[92:93], 0
	v_mov_b64_e32 v[94:95], 0
	v_mov_b64_e32 v[96:97], 0
	v_mov_b64_e32 v[98:99], 0
	v_mov_b64_e32 v[100:101], 0
	v_mov_b64_e32 v[102:103], 0
	v_mov_b64_e32 v[104:105], 0
	v_mov_b64_e32 v[106:107], 0
	v_mov_b64_e32 v[108:109], 0
	v_mov_b64_e32 v[110:111], 0
	v_mov_b64_e32 v[112:113], 0
	v_mov_b64_e32 v[114:115], 0
	v_mov_b64_e32 v[116:117], 0
	v_mov_b64_e32 v[118:119], 0
	v_mov_b64_e32 v[120:121], 0
	v_mov_b64_e32 v[122:123], 0
	v_mov_b64_e32 v[124:125], 0
	v_mov_b64_e32 v[126:127], 0
	v_mov_b64_e32 v[128:129], 0
	.p2align	6

.LBB11_1628:
	v_readlane_b32 s0, v243, 39
	s_add_u32 s18, s0, s44
	v_readlane_b32 s0, v243, 40
	s_addc_u32 s19, s0, 0
	s_and_b64 s[0:1], s[16:17], exec
	s_cselect_b32 s8, s19, s23
	s_cselect_b32 s9, s18, s22
	s_add_u32 s20, s30, s43
	s_addc_u32 s21, s31, 0
	s_and_b64 s[0:1], s[16:17], exec
	s_cselect_b32 s40, s21, s25
	s_cselect_b32 s46, s20, s24
	s_add_u32 s22, s22, 0x80080
	s_addc_u32 s23, s23, 0
	s_add_u32 s47, s24, 0x100
	v_mov_b32_e32 v2, 0
	s_addc_u32 s56, s25, 0
	s_mov_b32 s57, -2
	s_waitcnt lgkmcnt(0)
	v_mov_b64_e32 v[2:3], 0
	v_mov_b64_e32 v[4:5], 0
	v_mov_b64_e32 v[6:7], 0
	v_mov_b64_e32 v[8:9], 0
	v_mov_b64_e32 v[10:11], 0
	v_mov_b64_e32 v[12:13], 0
	v_mov_b64_e32 v[14:15], 0
	v_mov_b64_e32 v[16:17], 0
	v_mov_b64_e32 v[18:19], 0
	v_mov_b64_e32 v[20:21], 0
	v_mov_b64_e32 v[22:23], 0
	v_mov_b64_e32 v[24:25], 0
	v_mov_b64_e32 v[26:27], 0
	v_mov_b64_e32 v[28:29], 0
	v_mov_b64_e32 v[30:31], 0
	v_mov_b64_e32 v[32:33], 0
	v_mov_b64_e32 v[34:35], 0
	v_mov_b64_e32 v[36:37], 0
	v_mov_b64_e32 v[38:39], 0
	v_mov_b64_e32 v[40:41], 0
	v_mov_b64_e32 v[42:43], 0
	v_mov_b64_e32 v[44:45], 0
	v_mov_b64_e32 v[46:47], 0
	v_mov_b64_e32 v[48:49], 0
	v_mov_b64_e32 v[50:51], 0
	v_mov_b64_e32 v[52:53], 0
	v_mov_b64_e32 v[54:55], 0
	v_mov_b64_e32 v[56:57], 0
	v_mov_b64_e32 v[58:59], 0
	v_mov_b64_e32 v[60:61], 0
	v_mov_b64_e32 v[62:63], 0
	v_mov_b64_e32 v[64:65], 0
	v_mov_b64_e32 v[66:67], 0
	v_mov_b64_e32 v[68:69], 0
	v_mov_b64_e32 v[70:71], 0
	v_mov_b64_e32 v[72:73], 0
	v_mov_b64_e32 v[74:75], 0
	v_mov_b64_e32 v[76:77], 0
	v_mov_b64_e32 v[78:79], 0
	v_mov_b64_e32 v[80:81], 0
	v_mov_b64_e32 v[82:83], 0
	v_mov_b64_e32 v[84:85], 0
	v_mov_b64_e32 v[86:87], 0
	v_mov_b64_e32 v[88:89], 0
	v_mov_b64_e32 v[90:91], 0
	v_mov_b64_e32 v[92:93], 0
	v_mov_b64_e32 v[94:95], 0
	v_mov_b64_e32 v[96:97], 0
	v_mov_b64_e32 v[98:99], 0
	v_mov_b64_e32 v[100:101], 0
	v_mov_b64_e32 v[102:103], 0
	v_mov_b64_e32 v[104:105], 0
	v_mov_b64_e32 v[106:107], 0
	v_mov_b64_e32 v[108:109], 0
	v_mov_b64_e32 v[110:111], 0
	v_mov_b64_e32 v[112:113], 0
	v_mov_b64_e32 v[114:115], 0
	v_mov_b64_e32 v[116:117], 0
	v_mov_b64_e32 v[118:119], 0
	v_mov_b64_e32 v[120:121], 0
	v_mov_b64_e32 v[122:123], 0
	v_mov_b64_e32 v[124:125], 0
	v_mov_b64_e32 v[126:127], 0
	v_mov_b64_e32 v[128:129], 0
	.p2align	6

.LBB11_1868:
	s_add_u32 s20, s66, s40
	s_addc_u32 s21, s67, 0
	s_and_b64 s[0:1], exec, s[18:19]
	s_cselect_b32 s43, s21, s25
	s_cselect_b32 s44, s20, s24
	s_add_u32 s22, s34, s22
	s_addc_u32 s23, s35, s23
	s_and_b64 s[0:1], exec, s[18:19]
	s_cselect_b32 s45, s23, s11
	s_cselect_b32 s46, s22, s10
	s_add_u32 s24, s24, 0x40080
	s_addc_u32 s25, s25, 0
	s_add_u32 s47, s10, 0x100
	v_mov_b32_e32 v2, 0
	s_addc_u32 s56, s11, 0
	s_mov_b32 s57, -2
	v_mov_b64_e32 v[2:3], 0
	v_mov_b64_e32 v[4:5], 0
	v_mov_b64_e32 v[6:7], 0
	v_mov_b64_e32 v[8:9], 0
	v_mov_b64_e32 v[10:11], 0
	v_mov_b64_e32 v[12:13], 0
	v_mov_b64_e32 v[14:15], 0
	v_mov_b64_e32 v[16:17], 0
	v_mov_b64_e32 v[18:19], 0
	v_mov_b64_e32 v[20:21], 0
	v_mov_b64_e32 v[22:23], 0
	v_mov_b64_e32 v[24:25], 0
	v_mov_b64_e32 v[26:27], 0
	v_mov_b64_e32 v[28:29], 0
	v_mov_b64_e32 v[30:31], 0
	v_mov_b64_e32 v[32:33], 0
	v_mov_b64_e32 v[34:35], 0
	v_mov_b64_e32 v[36:37], 0
	v_mov_b64_e32 v[38:39], 0
	v_mov_b64_e32 v[40:41], 0
	v_mov_b64_e32 v[42:43], 0
	v_mov_b64_e32 v[44:45], 0
	v_mov_b64_e32 v[46:47], 0
	v_mov_b64_e32 v[48:49], 0
	v_mov_b64_e32 v[50:51], 0
	v_mov_b64_e32 v[52:53], 0
	v_mov_b64_e32 v[54:55], 0
	v_mov_b64_e32 v[56:57], 0
	v_mov_b64_e32 v[58:59], 0
	v_mov_b64_e32 v[60:61], 0
	v_mov_b64_e32 v[62:63], 0
	v_mov_b64_e32 v[64:65], 0
	v_mov_b64_e32 v[66:67], 0
	v_mov_b64_e32 v[68:69], 0
	v_mov_b64_e32 v[70:71], 0
	v_mov_b64_e32 v[72:73], 0
	v_mov_b64_e32 v[74:75], 0
	v_mov_b64_e32 v[76:77], 0
	v_mov_b64_e32 v[78:79], 0
	v_mov_b64_e32 v[80:81], 0
	v_mov_b64_e32 v[82:83], 0
	v_mov_b64_e32 v[84:85], 0
	v_mov_b64_e32 v[86:87], 0
	v_mov_b64_e32 v[88:89], 0
	v_mov_b64_e32 v[90:91], 0
	v_mov_b64_e32 v[92:93], 0
	v_mov_b64_e32 v[94:95], 0
	v_mov_b64_e32 v[96:97], 0
	v_mov_b64_e32 v[98:99], 0
	v_mov_b64_e32 v[100:101], 0
	v_mov_b64_e32 v[102:103], 0
	v_mov_b64_e32 v[104:105], 0
	v_mov_b64_e32 v[106:107], 0
	v_mov_b64_e32 v[108:109], 0
	v_mov_b64_e32 v[110:111], 0
	v_mov_b64_e32 v[112:113], 0
	v_mov_b64_e32 v[114:115], 0
	v_mov_b64_e32 v[116:117], 0
	v_mov_b64_e32 v[118:119], 0
	v_mov_b64_e32 v[120:121], 0
	v_mov_b64_e32 v[122:123], 0
	v_mov_b64_e32 v[124:125], 0
	v_mov_b64_e32 v[126:127], 0
	v_mov_b64_e32 v[128:129], 0
	.p2align	6

.LBB11_2044:
	s_add_u32 s18, s78, s91
	s_addc_u32 s19, s79, 0
	s_and_b64 s[0:1], s[20:21], exec
	s_cselect_b32 s7, s19, s27
	s_cselect_b32 s8, s18, s26
	s_add_u32 s22, s44, s29
	s_addc_u32 s23, s45, 0
	s_and_b64 s[0:1], s[20:21], exec
	v_mov_b32_e32 v2, 0
	s_cselect_b32 s9, s23, s25
	s_cselect_b32 s68, s22, s24
	s_mov_b64 s[34:35], 0
	s_mov_b64 s[30:31], -1
	s_mov_b64 s[10:11], 0
	v_mov_b64_e32 v[2:3], 0
	v_mov_b64_e32 v[4:5], 0
	v_mov_b64_e32 v[6:7], 0
	v_mov_b64_e32 v[8:9], 0
	v_mov_b64_e32 v[10:11], 0
	v_mov_b64_e32 v[12:13], 0
	v_mov_b64_e32 v[14:15], 0
	v_mov_b64_e32 v[16:17], 0
	v_mov_b64_e32 v[18:19], 0
	v_mov_b64_e32 v[20:21], 0
	v_mov_b64_e32 v[22:23], 0
	v_mov_b64_e32 v[24:25], 0
	v_mov_b64_e32 v[26:27], 0
	v_mov_b64_e32 v[28:29], 0
	v_mov_b64_e32 v[30:31], 0
	v_mov_b64_e32 v[32:33], 0
	v_mov_b64_e32 v[34:35], 0
	v_mov_b64_e32 v[36:37], 0
	v_mov_b64_e32 v[38:39], 0
	v_mov_b64_e32 v[40:41], 0
	v_mov_b64_e32 v[42:43], 0
	v_mov_b64_e32 v[44:45], 0
	v_mov_b64_e32 v[46:47], 0
	v_mov_b64_e32 v[48:49], 0
	v_mov_b64_e32 v[50:51], 0
	v_mov_b64_e32 v[52:53], 0
	v_mov_b64_e32 v[54:55], 0
	v_mov_b64_e32 v[56:57], 0
	v_mov_b64_e32 v[58:59], 0
	v_mov_b64_e32 v[60:61], 0
	v_mov_b64_e32 v[62:63], 0
	v_mov_b64_e32 v[64:65], 0
	v_mov_b64_e32 v[66:67], 0
	v_mov_b64_e32 v[68:69], 0
	v_mov_b64_e32 v[70:71], 0
	v_mov_b64_e32 v[72:73], 0
	v_mov_b64_e32 v[74:75], 0
	v_mov_b64_e32 v[76:77], 0
	v_mov_b64_e32 v[78:79], 0
	v_mov_b64_e32 v[80:81], 0
	v_mov_b64_e32 v[82:83], 0
	v_mov_b64_e32 v[84:85], 0
	v_mov_b64_e32 v[86:87], 0
	v_mov_b64_e32 v[88:89], 0
	v_mov_b64_e32 v[90:91], 0
	v_mov_b64_e32 v[92:93], 0
	v_mov_b64_e32 v[94:95], 0
	v_mov_b64_e32 v[96:97], 0
	v_mov_b64_e32 v[98:99], 0
	v_mov_b64_e32 v[100:101], 0
	v_mov_b64_e32 v[102:103], 0
	v_mov_b64_e32 v[104:105], 0
	v_mov_b64_e32 v[106:107], 0
	v_mov_b64_e32 v[108:109], 0
	v_mov_b64_e32 v[110:111], 0
	v_mov_b64_e32 v[112:113], 0
	v_mov_b64_e32 v[114:115], 0
	v_mov_b64_e32 v[116:117], 0
	v_mov_b64_e32 v[118:119], 0
	v_mov_b64_e32 v[120:121], 0
	v_mov_b64_e32 v[122:123], 0
	v_mov_b64_e32 v[124:125], 0
	v_mov_b64_e32 v[126:127], 0
	v_mov_b64_e32 v[128:129], 0
	.p2align	6

.LBB11_2092:
	s_add_u32 s16, s80, s9
	s_addc_u32 s17, s81, 0
	s_and_b64 s[0:1], s[18:19], exec
	s_cselect_b32 s58, s17, s25
	s_cselect_b32 s59, s16, s24
	s_add_u32 s20, s6, s56
	s_addc_u32 s21, s7, 0
	s_and_b64 s[0:1], s[18:19], exec
	v_mov_b32_e32 v2, 0
	s_cselect_b32 s60, s21, s23
	s_cselect_b32 s68, s20, s22
	s_mov_b64 s[28:29], 0
	s_mov_b64 s[26:27], -1
	s_mov_b64 s[10:11], 0
	v_mov_b64_e32 v[2:3], 0
	v_mov_b64_e32 v[4:5], 0
	v_mov_b64_e32 v[6:7], 0
	v_mov_b64_e32 v[8:9], 0
	v_mov_b64_e32 v[10:11], 0
	v_mov_b64_e32 v[12:13], 0
	v_mov_b64_e32 v[14:15], 0
	v_mov_b64_e32 v[16:17], 0
	v_mov_b64_e32 v[18:19], 0
	v_mov_b64_e32 v[20:21], 0
	v_mov_b64_e32 v[22:23], 0
	v_mov_b64_e32 v[24:25], 0
	v_mov_b64_e32 v[26:27], 0
	v_mov_b64_e32 v[28:29], 0
	v_mov_b64_e32 v[30:31], 0
	v_mov_b64_e32 v[32:33], 0
	v_mov_b64_e32 v[34:35], 0
	v_mov_b64_e32 v[36:37], 0
	v_mov_b64_e32 v[38:39], 0
	v_mov_b64_e32 v[40:41], 0
	v_mov_b64_e32 v[42:43], 0
	v_mov_b64_e32 v[44:45], 0
	v_mov_b64_e32 v[46:47], 0
	v_mov_b64_e32 v[48:49], 0
	v_mov_b64_e32 v[50:51], 0
	v_mov_b64_e32 v[52:53], 0
	v_mov_b64_e32 v[54:55], 0
	v_mov_b64_e32 v[56:57], 0
	v_mov_b64_e32 v[58:59], 0
	v_mov_b64_e32 v[60:61], 0
	v_mov_b64_e32 v[62:63], 0
	v_mov_b64_e32 v[64:65], 0
	v_mov_b64_e32 v[66:67], 0
	v_mov_b64_e32 v[68:69], 0
	v_mov_b64_e32 v[70:71], 0
	v_mov_b64_e32 v[72:73], 0
	v_mov_b64_e32 v[74:75], 0
	v_mov_b64_e32 v[76:77], 0
	v_mov_b64_e32 v[78:79], 0
	v_mov_b64_e32 v[80:81], 0
	v_mov_b64_e32 v[82:83], 0
	v_mov_b64_e32 v[84:85], 0
	v_mov_b64_e32 v[86:87], 0
	v_mov_b64_e32 v[88:89], 0
	v_mov_b64_e32 v[90:91], 0
	v_mov_b64_e32 v[92:93], 0
	v_mov_b64_e32 v[94:95], 0
	v_mov_b64_e32 v[96:97], 0
	v_mov_b64_e32 v[98:99], 0
	v_mov_b64_e32 v[100:101], 0
	v_mov_b64_e32 v[102:103], 0
	v_mov_b64_e32 v[104:105], 0
	v_mov_b64_e32 v[106:107], 0
	v_mov_b64_e32 v[108:109], 0
	v_mov_b64_e32 v[110:111], 0
	v_mov_b64_e32 v[112:113], 0
	v_mov_b64_e32 v[114:115], 0
	v_mov_b64_e32 v[116:117], 0
	v_mov_b64_e32 v[118:119], 0
	v_mov_b64_e32 v[120:121], 0
	v_mov_b64_e32 v[122:123], 0
	v_mov_b64_e32 v[124:125], 0
	v_mov_b64_e32 v[126:127], 0
	v_mov_b64_e32 v[128:129], 0
	.p2align	6

.LBB11_2328:
	s_add_u32 s18, s82, s43
	s_addc_u32 s19, s83, 0
	s_and_b64 s[0:1], s[16:17], exec
	s_cselect_b32 s8, s19, s23
	s_cselect_b32 s9, s18, s22
	s_add_u32 s20, s30, s42
	s_addc_u32 s21, s31, 0
	s_and_b64 s[0:1], s[16:17], exec
	s_cselect_b32 s45, s21, s25
	s_cselect_b32 s46, s20, s24
	s_add_u32 s22, s22, 0x40080
	s_addc_u32 s23, s23, 0
	s_add_u32 s47, s24, 0x100
	v_mov_b32_e32 v2, 0
	s_addc_u32 s56, s25, 0
	s_mov_b32 s57, -2
	s_waitcnt lgkmcnt(0)
	v_mov_b64_e32 v[2:3], 0
	v_mov_b64_e32 v[4:5], 0
	v_mov_b64_e32 v[6:7], 0
	v_mov_b64_e32 v[8:9], 0
	v_mov_b64_e32 v[10:11], 0
	v_mov_b64_e32 v[12:13], 0
	v_mov_b64_e32 v[14:15], 0
	v_mov_b64_e32 v[16:17], 0
	v_mov_b64_e32 v[18:19], 0
	v_mov_b64_e32 v[20:21], 0
	v_mov_b64_e32 v[22:23], 0
	v_mov_b64_e32 v[24:25], 0
	v_mov_b64_e32 v[26:27], 0
	v_mov_b64_e32 v[28:29], 0
	v_mov_b64_e32 v[30:31], 0
	v_mov_b64_e32 v[32:33], 0
	v_mov_b64_e32 v[34:35], 0
	v_mov_b64_e32 v[36:37], 0
	v_mov_b64_e32 v[38:39], 0
	v_mov_b64_e32 v[40:41], 0
	v_mov_b64_e32 v[42:43], 0
	v_mov_b64_e32 v[44:45], 0
	v_mov_b64_e32 v[46:47], 0
	v_mov_b64_e32 v[48:49], 0
	v_mov_b64_e32 v[50:51], 0
	v_mov_b64_e32 v[52:53], 0
	v_mov_b64_e32 v[54:55], 0
	v_mov_b64_e32 v[56:57], 0
	v_mov_b64_e32 v[58:59], 0
	v_mov_b64_e32 v[60:61], 0
	v_mov_b64_e32 v[62:63], 0
	v_mov_b64_e32 v[64:65], 0
	v_mov_b64_e32 v[66:67], 0
	v_mov_b64_e32 v[68:69], 0
	v_mov_b64_e32 v[70:71], 0
	v_mov_b64_e32 v[72:73], 0
	v_mov_b64_e32 v[74:75], 0
	v_mov_b64_e32 v[76:77], 0
	v_mov_b64_e32 v[78:79], 0
	v_mov_b64_e32 v[80:81], 0
	v_mov_b64_e32 v[82:83], 0
	v_mov_b64_e32 v[84:85], 0
	v_mov_b64_e32 v[86:87], 0
	v_mov_b64_e32 v[88:89], 0
	v_mov_b64_e32 v[90:91], 0
	v_mov_b64_e32 v[92:93], 0
	v_mov_b64_e32 v[94:95], 0
	v_mov_b64_e32 v[96:97], 0
	v_mov_b64_e32 v[98:99], 0
	v_mov_b64_e32 v[100:101], 0
	v_mov_b64_e32 v[102:103], 0
	v_mov_b64_e32 v[104:105], 0
	v_mov_b64_e32 v[106:107], 0
	v_mov_b64_e32 v[108:109], 0
	v_mov_b64_e32 v[110:111], 0
	v_mov_b64_e32 v[112:113], 0
	v_mov_b64_e32 v[114:115], 0
	v_mov_b64_e32 v[116:117], 0
	v_mov_b64_e32 v[118:119], 0
	v_mov_b64_e32 v[120:121], 0
	v_mov_b64_e32 v[122:123], 0
	v_mov_b64_e32 v[124:125], 0
	v_mov_b64_e32 v[126:127], 0
	v_mov_b64_e32 v[128:129], 0
	.p2align	6

.LBB11_2566:
	s_add_u32 s22, s66, s45
	s_addc_u32 s23, s67, 0
	s_and_b64 s[0:1], s[12:13], exec
	s_cselect_b32 s9, s23, s27
	s_cselect_b32 s47, s22, s26
	s_add_u32 s24, s14, s44
	s_addc_u32 s25, s15, 0
	s_and_b64 s[0:1], s[12:13], exec
	s_cselect_b32 s56, s25, s29
	s_cselect_b32 s57, s24, s28
	s_add_u32 s26, s26, 0x40080
	s_addc_u32 s27, s27, 0
	s_add_u32 s58, s28, 0x100
	v_mov_b32_e32 v2, 0
	s_addc_u32 s59, s29, 0
	s_mov_b32 s68, -2
	v_mov_b64_e32 v[2:3], 0
	v_mov_b64_e32 v[4:5], 0
	v_mov_b64_e32 v[6:7], 0
	v_mov_b64_e32 v[8:9], 0
	v_mov_b64_e32 v[10:11], 0
	v_mov_b64_e32 v[12:13], 0
	v_mov_b64_e32 v[14:15], 0
	v_mov_b64_e32 v[16:17], 0
	v_mov_b64_e32 v[18:19], 0
	v_mov_b64_e32 v[20:21], 0
	v_mov_b64_e32 v[22:23], 0
	v_mov_b64_e32 v[24:25], 0
	v_mov_b64_e32 v[26:27], 0
	v_mov_b64_e32 v[28:29], 0
	v_mov_b64_e32 v[30:31], 0
	v_mov_b64_e32 v[32:33], 0
	v_mov_b64_e32 v[34:35], 0
	v_mov_b64_e32 v[36:37], 0
	v_mov_b64_e32 v[38:39], 0
	v_mov_b64_e32 v[40:41], 0
	v_mov_b64_e32 v[42:43], 0
	v_mov_b64_e32 v[44:45], 0
	v_mov_b64_e32 v[46:47], 0
	v_mov_b64_e32 v[48:49], 0
	v_mov_b64_e32 v[50:51], 0
	v_mov_b64_e32 v[52:53], 0
	v_mov_b64_e32 v[54:55], 0
	v_mov_b64_e32 v[56:57], 0
	v_mov_b64_e32 v[58:59], 0
	v_mov_b64_e32 v[60:61], 0
	v_mov_b64_e32 v[62:63], 0
	v_mov_b64_e32 v[64:65], 0
	v_mov_b64_e32 v[66:67], 0
	v_mov_b64_e32 v[68:69], 0
	v_mov_b64_e32 v[70:71], 0
	v_mov_b64_e32 v[72:73], 0
	v_mov_b64_e32 v[74:75], 0
	v_mov_b64_e32 v[76:77], 0
	v_mov_b64_e32 v[78:79], 0
	v_mov_b64_e32 v[80:81], 0
	v_mov_b64_e32 v[82:83], 0
	v_mov_b64_e32 v[84:85], 0
	v_mov_b64_e32 v[86:87], 0
	v_mov_b64_e32 v[88:89], 0
	v_mov_b64_e32 v[90:91], 0
	v_mov_b64_e32 v[92:93], 0
	v_mov_b64_e32 v[94:95], 0
	v_mov_b64_e32 v[96:97], 0
	v_mov_b64_e32 v[98:99], 0
	v_mov_b64_e32 v[100:101], 0
	v_mov_b64_e32 v[102:103], 0
	v_mov_b64_e32 v[104:105], 0
	v_mov_b64_e32 v[106:107], 0
	v_mov_b64_e32 v[108:109], 0
	v_mov_b64_e32 v[110:111], 0
	v_mov_b64_e32 v[112:113], 0
	v_mov_b64_e32 v[114:115], 0
	v_mov_b64_e32 v[116:117], 0
	v_mov_b64_e32 v[118:119], 0
	v_mov_b64_e32 v[120:121], 0
	v_mov_b64_e32 v[122:123], 0
	v_mov_b64_e32 v[124:125], 0
	v_mov_b64_e32 v[126:127], 0
	v_mov_b64_e32 v[128:129], 0
	.p2align	6

.LBB11_2769:
	s_add_u32 s18, s4, s45
	s_addc_u32 s19, s5, 0
	s_and_b64 s[0:1], s[16:17], exec
	s_cselect_b32 s8, s19, s23
	s_cselect_b32 s9, s18, s22
	s_add_u32 s20, s38, s44
	s_addc_u32 s21, s39, 0
	s_and_b64 s[0:1], s[16:17], exec
	s_cselect_b32 s47, s21, s25
	s_cselect_b32 s56, s20, s24
	s_add_u32 s57, s24, 0x100
	v_mov_b32_e32 v2, 0
	s_addc_u32 s58, s25, 0
	s_mov_b32 s59, -2
	s_waitcnt lgkmcnt(0)
	v_mov_b64_e32 v[2:3], 0
	v_mov_b64_e32 v[4:5], 0
	v_mov_b64_e32 v[6:7], 0
	v_mov_b64_e32 v[8:9], 0
	v_mov_b64_e32 v[10:11], 0
	v_mov_b64_e32 v[12:13], 0
	v_mov_b64_e32 v[14:15], 0
	v_mov_b64_e32 v[16:17], 0
	v_mov_b64_e32 v[18:19], 0
	v_mov_b64_e32 v[20:21], 0
	v_mov_b64_e32 v[22:23], 0
	v_mov_b64_e32 v[24:25], 0
	v_mov_b64_e32 v[26:27], 0
	v_mov_b64_e32 v[28:29], 0
	v_mov_b64_e32 v[30:31], 0
	v_mov_b64_e32 v[32:33], 0
	v_mov_b64_e32 v[34:35], 0
	v_mov_b64_e32 v[36:37], 0
	v_mov_b64_e32 v[38:39], 0
	v_mov_b64_e32 v[40:41], 0
	v_mov_b64_e32 v[42:43], 0
	v_mov_b64_e32 v[44:45], 0
	v_mov_b64_e32 v[46:47], 0
	v_mov_b64_e32 v[48:49], 0
	v_mov_b64_e32 v[50:51], 0
	v_mov_b64_e32 v[52:53], 0
	v_mov_b64_e32 v[54:55], 0
	v_mov_b64_e32 v[56:57], 0
	v_mov_b64_e32 v[58:59], 0
	v_mov_b64_e32 v[60:61], 0
	v_mov_b64_e32 v[62:63], 0
	v_mov_b64_e32 v[64:65], 0
	v_mov_b64_e32 v[66:67], 0
	v_mov_b64_e32 v[68:69], 0
	v_mov_b64_e32 v[70:71], 0
	v_mov_b64_e32 v[72:73], 0
	v_mov_b64_e32 v[74:75], 0
	v_mov_b64_e32 v[76:77], 0
	v_mov_b64_e32 v[78:79], 0
	v_mov_b64_e32 v[80:81], 0
	v_mov_b64_e32 v[82:83], 0
	v_mov_b64_e32 v[84:85], 0
	v_mov_b64_e32 v[86:87], 0
	v_mov_b64_e32 v[88:89], 0
	v_mov_b64_e32 v[90:91], 0
	v_mov_b64_e32 v[92:93], 0
	v_mov_b64_e32 v[94:95], 0
	v_mov_b64_e32 v[96:97], 0
	v_mov_b64_e32 v[98:99], 0
	v_mov_b64_e32 v[100:101], 0
	v_mov_b64_e32 v[102:103], 0
	v_mov_b64_e32 v[104:105], 0
	v_mov_b64_e32 v[106:107], 0
	v_mov_b64_e32 v[108:109], 0
	v_mov_b64_e32 v[110:111], 0
	v_mov_b64_e32 v[112:113], 0
	v_mov_b64_e32 v[114:115], 0
	v_mov_b64_e32 v[116:117], 0
	v_mov_b64_e32 v[118:119], 0
	v_mov_b64_e32 v[120:121], 0
	v_mov_b64_e32 v[122:123], 0
	v_mov_b64_e32 v[124:125], 0
	v_mov_b64_e32 v[126:127], 0
	v_mov_b64_e32 v[128:129], 0
	.p2align	6
